# prologue adaLN modulation rewritten: per-wave K split on f32 MFMA 16x16x4 (exact f32), loads batched and double-buffered instead of one serialized load per k; LDS cross-wave reduce
# speedup vs baseline: 1.0227x; 1.0227x over previous
; #define LAS __attribute__((address_space(3)))
; __device__ __forceinline__ float siluf_(float x) { return x * __builtin_amdgcn_rcpf(1.f + __expf(-x)); }
; __device__ __forceinline__ void prologue_mod_item(const Args& a, LAS unsigned char* lds, int item, int tid) {
;     const int l = item / 96, n0 = (item % 96) * 64;
;     const float* W = a.in[9] + (size_t)l * DM * (6 * DM);
;     LAS float* sl = (LAS float*)lds;
;     const int col = tid & 63, kp = tid >> 6;
;     f32x2 acc[NSEQ / 2];
; #pragma unroll
;     for (int s = 0; s < NSEQ / 2; ++s) acc[s] = (f32x2){0.f, 0.f};
;     for (int half = 0; half < 2; ++half) {
;         __syncthreads();
;         for (int idx = tid; idx < 512 * NSEQ; idx += 512) { const int s = idx >> 9, kl = idx & 511, k = half * 512 + kl;
;             const float v = s < NPB ? a.in[6][s * DM + k] : a.in[7][(s - NPB) * DM + k];
;             sl[kl * NSEQ + s] = siluf_(v); }
;         __syncthreads();
; #pragma unroll 16
;         for (int kk = 0; kk < 64; ++kk) { const int kl = kp * 64 + kk;
;             const float w = __builtin_nontemporal_load(&W[(size_t)(half * 512 + kl) * (6 * DM) + n0 + col]);
;             const LAS f32x4* sp = (const LAS f32x4*)(sl + kl * NSEQ);
; #pragma unroll
;             for (int q = 0; q < NSEQ / 4; ++q) { const f32x4 sv = sp[q]; const f32x2 w2 = (f32x2){w, w};
;                 acc[2 * q] = __builtin_elementwise_fma((f32x2){sv[0], sv[1]}, w2, acc[2 * q]); acc[2 * q + 1] = __builtin_elementwise_fma((f32x2){sv[2], sv[3]}, w2, acc[2 * q + 1]); } }
.LBB0_104:
	s_cmpk_gt_i32 s52, 0xbf
	s_cbranch_scc1 .LBB0_117
	v_and_b32_e32 v200, 63, v166
	v_lshrrev_b32_e32 v201, 6, v166
	v_and_b32_e32 v202, 15, v200
	v_lshrrev_b32_e32 v203, 4, v200
	v_readfirstlane_b32 s3, v201
	v_lshlrev_b32_e32 v204, 12, v202
	v_lshl_or_b32 v204, v201, 9, v204
	v_lshl_or_b32 v204, v203, 5, v204
	v_add_u32_e32 v205, 0x10000, v204
	v_lshl_add_u32 v206, v201, 4, v203
	v_mul_u32_u24_e32 v206, 0x30000, v206
	v_mul_u32_u24_e32 v212, 16, v202
	v_add_u32_e32 v206, v206, v212
	v_mul_u32_u24_e32 v212, 4, v202
	v_mad_u32_u24 v212, v201, 64, v212
	v_mul_u32_u24_e32 v212, 0xd0, v212
	v_lshl_add_u32 v207, v203, 4, v212
	v_mul_u32_u24_e32 v212, 0xd0, v200
	v_lshl_add_u32 v208, v201, 4, v212
	v_add_u32_e32 v209, 0xd000, v208
	v_lshlrev_b32_e32 v210, 2, v200
	v_readlane_b32 s0, v252, 33
	v_readlane_b32 s1, v252, 34
	v_readlane_b32 s18, v252, 35
	v_readlane_b32 s19, v252, 36
	s_mov_b32 s15, s52
.Lmod_item:
	s_waitcnt vmcnt(0)
	s_cmp_ge_u32 s15, 96
	s_cselect_b32 s16, 1, 0
	s_mul_i32 s6, s16, 96
	s_sub_i32 s17, s15, s6
	s_mul_i32 s17, s17, 256
	v_readlane_b32 s8, v252, 7
	v_readlane_b32 s9, v252, 8
	s_mul_i32 s6, s16, 0x1800000
	s_add_u32 s8, s8, s6
	s_addc_u32 s9, s9, 0
	s_add_u32 s8, s8, s17
	s_addc_u32 s9, s9, 0
	v_readlane_b32 s6, v252, 9
	v_readlane_b32 s7, v252, 10
	s_mul_i32 s14, s16, 0x6000
	s_add_u32 s6, s6, s14
	s_addc_u32 s7, s7, 0
	s_add_u32 s6, s6, s17
	s_addc_u32 s7, s7, 0
	s_mul_i32 s14, s16, 0x120000
	s_add_u32 s10, s26, 0x5400000
	s_addc_u32 s11, s27, 0
	s_add_u32 s10, s10, s14
	s_addc_u32 s11, s11, 0
	s_add_u32 s10, s10, s17
	s_addc_u32 s11, s11, 0
	s_mul_i32 s14, s3, 0x18000
	s_add_u32 s10, s10, s14
	s_addc_u32 s11, s11, 0
	global_load_dwordx4 v[120:123], v204, s[0:1]
	global_load_dwordx4 v[124:127], v204, s[0:1] offset:16
	global_load_dwordx4 v[128:131], v204, s[18:19]
	global_load_dwordx4 v[132:135], v204, s[18:19] offset:16
	global_load_dwordx4 v[136:139], v205, s[18:19]
	global_load_dwordx4 v[140:143], v205, s[18:19] offset:16
	global_load_dwordx4 v[168:171], v206, s[8:9] nt
	s_add_u32 s8, s8, 0x6000
	s_addc_u32 s9, s9, 0
	global_load_dwordx4 v[172:175], v206, s[8:9] nt
	s_add_u32 s8, s8, 0x6000
	s_addc_u32 s9, s9, 0
	global_load_dwordx4 v[176:179], v206, s[8:9] nt
	s_add_u32 s8, s8, 0x6000
	s_addc_u32 s9, s9, 0
	global_load_dwordx4 v[180:183], v206, s[8:9] nt
	s_add_u32 s8, s8, 0x6000
	s_addc_u32 s9, s9, 0
	global_load_dwordx4 v[184:187], v206, s[8:9] nt
	s_add_u32 s8, s8, 0x6000
	s_addc_u32 s9, s9, 0
	global_load_dwordx4 v[188:191], v206, s[8:9] nt
	s_add_u32 s8, s8, 0x6000
	s_addc_u32 s9, s9, 0
	global_load_dwordx4 v[192:195], v206, s[8:9] nt
	s_add_u32 s8, s8, 0x6000
	s_addc_u32 s9, s9, 0
	global_load_dwordx4 v[196:199], v206, s[8:9] nt
	s_add_u32 s8, s8, 0x96000
	s_addc_u32 s9, s9, 0
	global_load_dword v211, v210, s[6:7]
	global_load_dwordx4 v[148:151], v204, s[0:1] offset:128
	global_load_dwordx4 v[152:155], v204, s[0:1] offset:144
	global_load_dwordx4 v[156:159], v204, s[18:19] offset:128
	global_load_dwordx4 v[160:163], v204, s[18:19] offset:144
	global_load_dwordx4 v[34:37], v205, s[18:19] offset:128
	global_load_dwordx4 v[38:41], v205, s[18:19] offset:144
	global_load_dwordx4 v[216:219], v206, s[8:9] nt
	s_add_u32 s8, s8, 0x6000
	s_addc_u32 s9, s9, 0
	global_load_dwordx4 v[220:223], v206, s[8:9] nt
	s_add_u32 s8, s8, 0x6000
	s_addc_u32 s9, s9, 0
	global_load_dwordx4 v[224:227], v206, s[8:9] nt
	s_add_u32 s8, s8, 0x6000
	s_addc_u32 s9, s9, 0
	global_load_dwordx4 v[228:231], v206, s[8:9] nt
	s_add_u32 s8, s8, 0x6000
	s_addc_u32 s9, s9, 0
	global_load_dwordx4 v[232:235], v206, s[8:9] nt
	s_add_u32 s8, s8, 0x6000
	s_addc_u32 s9, s9, 0
	global_load_dwordx4 v[236:239], v206, s[8:9] nt
	s_add_u32 s8, s8, 0x6000
	s_addc_u32 s9, s9, 0
	global_load_dwordx4 v[240:243], v206, s[8:9] nt
	s_add_u32 s8, s8, 0x6000
	s_addc_u32 s9, s9, 0
	global_load_dwordx4 v[244:247], v206, s[8:9] nt
	s_add_u32 s8, s8, 0x96000
	s_addc_u32 s9, s9, 0
	s_waitcnt vmcnt(28)
	v_mul_f32_e32 v212, 0xbfb8aa3b, v120
	v_mul_f32_e32 v213, 0xbfb8aa3b, v121
	v_mul_f32_e32 v248, 0xbfb8aa3b, v122
	v_mul_f32_e32 v249, 0xbfb8aa3b, v123
	v_exp_f32_e32 v212, v212
	v_exp_f32_e32 v213, v213
	v_exp_f32_e32 v248, v248
	v_exp_f32_e32 v249, v249
	v_add_f32_e32 v212, 1.0, v212
	v_add_f32_e32 v213, 1.0, v213
	v_add_f32_e32 v248, 1.0, v248
	v_add_f32_e32 v249, 1.0, v249
	v_rcp_f32_e32 v212, v212
	v_rcp_f32_e32 v213, v213
	v_rcp_f32_e32 v248, v248
	v_rcp_f32_e32 v249, v249
	v_mul_f32_e32 v120, v120, v212
	v_mul_f32_e32 v121, v121, v213
	v_mul_f32_e32 v122, v122, v248
	v_mul_f32_e32 v123, v123, v249
	s_waitcnt vmcnt(27)
	v_mul_f32_e32 v212, 0xbfb8aa3b, v124
	v_mul_f32_e32 v213, 0xbfb8aa3b, v125
	v_mul_f32_e32 v248, 0xbfb8aa3b, v126
	v_mul_f32_e32 v249, 0xbfb8aa3b, v127
	v_exp_f32_e32 v212, v212
	v_exp_f32_e32 v213, v213
	v_exp_f32_e32 v248, v248
	v_exp_f32_e32 v249, v249
	v_add_f32_e32 v212, 1.0, v212
	v_add_f32_e32 v213, 1.0, v213
	v_add_f32_e32 v248, 1.0, v248
	v_add_f32_e32 v249, 1.0, v249
	v_rcp_f32_e32 v212, v212
	v_rcp_f32_e32 v213, v213
	v_rcp_f32_e32 v248, v248
	v_rcp_f32_e32 v249, v249
	v_mul_f32_e32 v124, v124, v212
	v_mul_f32_e32 v125, v125, v213
	v_mul_f32_e32 v126, v126, v248
	v_mul_f32_e32 v127, v127, v249
	s_waitcnt vmcnt(26)
	v_mul_f32_e32 v212, 0xbfb8aa3b, v128
	v_mul_f32_e32 v213, 0xbfb8aa3b, v129
	v_mul_f32_e32 v248, 0xbfb8aa3b, v130
	v_mul_f32_e32 v249, 0xbfb8aa3b, v131
	v_exp_f32_e32 v212, v212
	v_exp_f32_e32 v213, v213
	v_exp_f32_e32 v248, v248
	v_exp_f32_e32 v249, v249
	v_add_f32_e32 v212, 1.0, v212
	v_add_f32_e32 v213, 1.0, v213
	v_add_f32_e32 v248, 1.0, v248
	v_add_f32_e32 v249, 1.0, v249
	v_rcp_f32_e32 v212, v212
	v_rcp_f32_e32 v213, v213
	v_rcp_f32_e32 v248, v248
	v_rcp_f32_e32 v249, v249
	v_mul_f32_e32 v128, v128, v212
	v_mul_f32_e32 v129, v129, v213
	v_mul_f32_e32 v130, v130, v248
	v_mul_f32_e32 v131, v131, v249
	s_waitcnt vmcnt(25)
; #define LAS __attribute__((address_space(3)))
; __device__ __forceinline__ void prologue_mod_item(const Args& a, LAS unsigned char* lds, int item, int tid) {
;     ...
;         for (int kk = 0; kk < 64; ++kk) { const int kl = kp * 64 + kk;
;             const float w = __builtin_nontemporal_load(&W[(size_t)(half * 512 + kl) * (6 * DM) + n0 + col]);
;             const LAS f32x4* sp = (const LAS f32x4*)(sl + kl * NSEQ);
; #pragma unroll
;             for (int q = 0; q < NSEQ / 4; ++q) { const f32x4 sv = sp[q]; const f32x2 w2 = (f32x2){w, w};
;                 acc[2 * q] = __builtin_elementwise_fma((f32x2){sv[0], sv[1]}, w2, acc[2 * q]); acc[2 * q + 1] = __builtin_elementwise_fma((f32x2){sv[2], sv[3]}, w2, acc[2 * q + 1]); } }
	v_mul_f32_e32 v212, 0xbfb8aa3b, v132
	v_mul_f32_e32 v213, 0xbfb8aa3b, v133
	v_mul_f32_e32 v248, 0xbfb8aa3b, v134
	v_mul_f32_e32 v249, 0xbfb8aa3b, v135
	v_exp_f32_e32 v212, v212
	v_exp_f32_e32 v213, v213
	v_exp_f32_e32 v248, v248
	v_exp_f32_e32 v249, v249
	v_add_f32_e32 v212, 1.0, v212
	v_add_f32_e32 v213, 1.0, v213
	v_add_f32_e32 v248, 1.0, v248
	v_add_f32_e32 v249, 1.0, v249
	v_rcp_f32_e32 v212, v212
	v_rcp_f32_e32 v213, v213
	v_rcp_f32_e32 v248, v248
	v_rcp_f32_e32 v249, v249
	v_mul_f32_e32 v132, v132, v212
	v_mul_f32_e32 v133, v133, v213
	v_mul_f32_e32 v134, v134, v248
	v_mul_f32_e32 v135, v135, v249
	s_waitcnt vmcnt(24)
	v_mul_f32_e32 v212, 0xbfb8aa3b, v136
	v_mul_f32_e32 v213, 0xbfb8aa3b, v137
	v_mul_f32_e32 v248, 0xbfb8aa3b, v138
	v_mul_f32_e32 v249, 0xbfb8aa3b, v139
	v_exp_f32_e32 v212, v212
	v_exp_f32_e32 v213, v213
	v_exp_f32_e32 v248, v248
	v_exp_f32_e32 v249, v249
	v_add_f32_e32 v212, 1.0, v212
	v_add_f32_e32 v213, 1.0, v213
	v_add_f32_e32 v248, 1.0, v248
	v_add_f32_e32 v249, 1.0, v249
	v_rcp_f32_e32 v212, v212
	v_rcp_f32_e32 v213, v213
	v_rcp_f32_e32 v248, v248
	v_rcp_f32_e32 v249, v249
	v_mul_f32_e32 v136, v136, v212
	v_mul_f32_e32 v137, v137, v213
	v_mul_f32_e32 v138, v138, v248
	v_mul_f32_e32 v139, v139, v249
	s_waitcnt vmcnt(23)
	v_mul_f32_e32 v212, 0xbfb8aa3b, v140
	v_mul_f32_e32 v213, 0xbfb8aa3b, v141
	v_mul_f32_e32 v248, 0xbfb8aa3b, v142
	v_mul_f32_e32 v249, 0xbfb8aa3b, v143
	v_exp_f32_e32 v212, v212
	v_exp_f32_e32 v213, v213
	v_exp_f32_e32 v248, v248
	v_exp_f32_e32 v249, v249
	v_add_f32_e32 v212, 1.0, v212
	v_add_f32_e32 v213, 1.0, v213
	v_add_f32_e32 v248, 1.0, v248
	v_add_f32_e32 v249, 1.0, v249
	v_rcp_f32_e32 v212, v212
	v_rcp_f32_e32 v213, v213
	v_rcp_f32_e32 v248, v248
	v_rcp_f32_e32 v249, v249
	v_mul_f32_e32 v140, v140, v212
	v_mul_f32_e32 v141, v141, v213
	v_mul_f32_e32 v142, v142, v248
	v_mul_f32_e32 v143, v143, v249
	s_waitcnt vmcnt(22)
	v_mfma_f32_16x16x4_f32 v[62:65], v120, v168, 0
	v_mfma_f32_16x16x4_f32 v[66:69], v120, v169, 0
	v_mfma_f32_16x16x4_f32 v[70:73], v120, v170, 0
	v_mfma_f32_16x16x4_f32 v[74:77], v120, v171, 0
	v_mfma_f32_16x16x4_f32 v[78:81], v128, v168, 0
	v_mfma_f32_16x16x4_f32 v[82:85], v128, v169, 0
	v_mfma_f32_16x16x4_f32 v[86:89], v128, v170, 0
	v_mfma_f32_16x16x4_f32 v[90:93], v128, v171, 0
	v_mfma_f32_16x16x4_f32 v[98:101], v136, v168, 0
	v_mfma_f32_16x16x4_f32 v[102:105], v136, v169, 0
	v_mfma_f32_16x16x4_f32 v[106:109], v136, v170, 0
	v_mfma_f32_16x16x4_f32 v[110:113], v136, v171, 0
	s_waitcnt vmcnt(21)
	v_mfma_f32_16x16x4_f32 v[62:65], v121, v172, v[62:65]
	v_mfma_f32_16x16x4_f32 v[66:69], v121, v173, v[66:69]
	v_mfma_f32_16x16x4_f32 v[70:73], v121, v174, v[70:73]
	v_mfma_f32_16x16x4_f32 v[74:77], v121, v175, v[74:77]
	v_mfma_f32_16x16x4_f32 v[78:81], v129, v172, v[78:81]
	v_mfma_f32_16x16x4_f32 v[82:85], v129, v173, v[82:85]
	v_mfma_f32_16x16x4_f32 v[86:89], v129, v174, v[86:89]
	v_mfma_f32_16x16x4_f32 v[90:93], v129, v175, v[90:93]
	v_mfma_f32_16x16x4_f32 v[98:101], v137, v172, v[98:101]
	v_mfma_f32_16x16x4_f32 v[102:105], v137, v173, v[102:105]
	v_mfma_f32_16x16x4_f32 v[106:109], v137, v174, v[106:109]
	v_mfma_f32_16x16x4_f32 v[110:113], v137, v175, v[110:113]
	s_waitcnt vmcnt(20)
	v_mfma_f32_16x16x4_f32 v[62:65], v122, v176, v[62:65]
	v_mfma_f32_16x16x4_f32 v[66:69], v122, v177, v[66:69]
	v_mfma_f32_16x16x4_f32 v[70:73], v122, v178, v[70:73]
	v_mfma_f32_16x16x4_f32 v[74:77], v122, v179, v[74:77]
	v_mfma_f32_16x16x4_f32 v[78:81], v130, v176, v[78:81]
	v_mfma_f32_16x16x4_f32 v[82:85], v130, v177, v[82:85]
	v_mfma_f32_16x16x4_f32 v[86:89], v130, v178, v[86:89]
	v_mfma_f32_16x16x4_f32 v[90:93], v130, v179, v[90:93]
	v_mfma_f32_16x16x4_f32 v[98:101], v138, v176, v[98:101]
	v_mfma_f32_16x16x4_f32 v[102:105], v138, v177, v[102:105]
	v_mfma_f32_16x16x4_f32 v[106:109], v138, v178, v[106:109]
	v_mfma_f32_16x16x4_f32 v[110:113], v138, v179, v[110:113]
	s_waitcnt vmcnt(19)
	v_mfma_f32_16x16x4_f32 v[62:65], v123, v180, v[62:65]
	v_mfma_f32_16x16x4_f32 v[66:69], v123, v181, v[66:69]
	v_mfma_f32_16x16x4_f32 v[70:73], v123, v182, v[70:73]
	v_mfma_f32_16x16x4_f32 v[74:77], v123, v183, v[74:77]
	v_mfma_f32_16x16x4_f32 v[78:81], v131, v180, v[78:81]
	v_mfma_f32_16x16x4_f32 v[82:85], v131, v181, v[82:85]
	v_mfma_f32_16x16x4_f32 v[86:89], v131, v182, v[86:89]
	v_mfma_f32_16x16x4_f32 v[90:93], v131, v183, v[90:93]
	v_mfma_f32_16x16x4_f32 v[98:101], v139, v180, v[98:101]
	v_mfma_f32_16x16x4_f32 v[102:105], v139, v181, v[102:105]
	v_mfma_f32_16x16x4_f32 v[106:109], v139, v182, v[106:109]
	v_mfma_f32_16x16x4_f32 v[110:113], v139, v183, v[110:113]
	s_waitcnt vmcnt(18)
	v_mfma_f32_16x16x4_f32 v[62:65], v124, v184, v[62:65]
	v_mfma_f32_16x16x4_f32 v[66:69], v124, v185, v[66:69]
	v_mfma_f32_16x16x4_f32 v[70:73], v124, v186, v[70:73]
	v_mfma_f32_16x16x4_f32 v[74:77], v124, v187, v[74:77]
	v_mfma_f32_16x16x4_f32 v[78:81], v132, v184, v[78:81]
	v_mfma_f32_16x16x4_f32 v[82:85], v132, v185, v[82:85]
	v_mfma_f32_16x16x4_f32 v[86:89], v132, v186, v[86:89]
	v_mfma_f32_16x16x4_f32 v[90:93], v132, v187, v[90:93]
	v_mfma_f32_16x16x4_f32 v[98:101], v140, v184, v[98:101]
	v_mfma_f32_16x16x4_f32 v[102:105], v140, v185, v[102:105]
	v_mfma_f32_16x16x4_f32 v[106:109], v140, v186, v[106:109]
	v_mfma_f32_16x16x4_f32 v[110:113], v140, v187, v[110:113]
	s_waitcnt vmcnt(17)
	v_mfma_f32_16x16x4_f32 v[62:65], v125, v188, v[62:65]
	v_mfma_f32_16x16x4_f32 v[66:69], v125, v189, v[66:69]
	v_mfma_f32_16x16x4_f32 v[70:73], v125, v190, v[70:73]
	v_mfma_f32_16x16x4_f32 v[74:77], v125, v191, v[74:77]
	v_mfma_f32_16x16x4_f32 v[78:81], v133, v188, v[78:81]
	v_mfma_f32_16x16x4_f32 v[82:85], v133, v189, v[82:85]
	v_mfma_f32_16x16x4_f32 v[86:89], v133, v190, v[86:89]
	v_mfma_f32_16x16x4_f32 v[90:93], v133, v191, v[90:93]
	v_mfma_f32_16x16x4_f32 v[98:101], v141, v188, v[98:101]
	v_mfma_f32_16x16x4_f32 v[102:105], v141, v189, v[102:105]
	v_mfma_f32_16x16x4_f32 v[106:109], v141, v190, v[106:109]
	v_mfma_f32_16x16x4_f32 v[110:113], v141, v191, v[110:113]
	s_waitcnt vmcnt(16)
; #define LAS __attribute__((address_space(3)))
; __device__ __forceinline__ void prologue_mod_item(const Args& a, LAS unsigned char* lds, int item, int tid) {
;     ...
;         for (int kk = 0; kk < 64; ++kk) { const int kl = kp * 64 + kk;
;             const float w = __builtin_nontemporal_load(&W[(size_t)(half * 512 + kl) * (6 * DM) + n0 + col]);
;             const LAS f32x4* sp = (const LAS f32x4*)(sl + kl * NSEQ);
; #pragma unroll
;             for (int q = 0; q < NSEQ / 4; ++q) { const f32x4 sv = sp[q]; const f32x2 w2 = (f32x2){w, w};
;                 acc[2 * q] = __builtin_elementwise_fma((f32x2){sv[0], sv[1]}, w2, acc[2 * q]); acc[2 * q + 1] = __builtin_elementwise_fma((f32x2){sv[2], sv[3]}, w2, acc[2 * q + 1]); } }
	v_mfma_f32_16x16x4_f32 v[62:65], v126, v192, v[62:65]
	v_mfma_f32_16x16x4_f32 v[66:69], v126, v193, v[66:69]
	v_mfma_f32_16x16x4_f32 v[70:73], v126, v194, v[70:73]
	v_mfma_f32_16x16x4_f32 v[74:77], v126, v195, v[74:77]
	v_mfma_f32_16x16x4_f32 v[78:81], v134, v192, v[78:81]
	v_mfma_f32_16x16x4_f32 v[82:85], v134, v193, v[82:85]
	v_mfma_f32_16x16x4_f32 v[86:89], v134, v194, v[86:89]
	v_mfma_f32_16x16x4_f32 v[90:93], v134, v195, v[90:93]
	v_mfma_f32_16x16x4_f32 v[98:101], v142, v192, v[98:101]
	v_mfma_f32_16x16x4_f32 v[102:105], v142, v193, v[102:105]
	v_mfma_f32_16x16x4_f32 v[106:109], v142, v194, v[106:109]
	v_mfma_f32_16x16x4_f32 v[110:113], v142, v195, v[110:113]
	s_waitcnt vmcnt(15)
	v_mfma_f32_16x16x4_f32 v[62:65], v127, v196, v[62:65]
	v_mfma_f32_16x16x4_f32 v[66:69], v127, v197, v[66:69]
	v_mfma_f32_16x16x4_f32 v[70:73], v127, v198, v[70:73]
	v_mfma_f32_16x16x4_f32 v[74:77], v127, v199, v[74:77]
	v_mfma_f32_16x16x4_f32 v[78:81], v135, v196, v[78:81]
	v_mfma_f32_16x16x4_f32 v[82:85], v135, v197, v[82:85]
	v_mfma_f32_16x16x4_f32 v[86:89], v135, v198, v[86:89]
	v_mfma_f32_16x16x4_f32 v[90:93], v135, v199, v[90:93]
	v_mfma_f32_16x16x4_f32 v[98:101], v143, v196, v[98:101]
	v_mfma_f32_16x16x4_f32 v[102:105], v143, v197, v[102:105]
	v_mfma_f32_16x16x4_f32 v[106:109], v143, v198, v[106:109]
	v_mfma_f32_16x16x4_f32 v[110:113], v143, v199, v[110:113]
	global_load_dwordx4 v[120:123], v204, s[0:1] offset:256
	global_load_dwordx4 v[124:127], v204, s[0:1] offset:272
	global_load_dwordx4 v[128:131], v204, s[18:19] offset:256
	global_load_dwordx4 v[132:135], v204, s[18:19] offset:272
	global_load_dwordx4 v[136:139], v205, s[18:19] offset:256
	global_load_dwordx4 v[140:143], v205, s[18:19] offset:272
	global_load_dwordx4 v[168:171], v206, s[8:9] nt
	s_add_u32 s8, s8, 0x6000
	s_addc_u32 s9, s9, 0
	global_load_dwordx4 v[172:175], v206, s[8:9] nt
	s_add_u32 s8, s8, 0x6000
	s_addc_u32 s9, s9, 0
	global_load_dwordx4 v[176:179], v206, s[8:9] nt
	s_add_u32 s8, s8, 0x6000
	s_addc_u32 s9, s9, 0
	global_load_dwordx4 v[180:183], v206, s[8:9] nt
	s_add_u32 s8, s8, 0x6000
	s_addc_u32 s9, s9, 0
	global_load_dwordx4 v[184:187], v206, s[8:9] nt
	s_add_u32 s8, s8, 0x6000
	s_addc_u32 s9, s9, 0
	global_load_dwordx4 v[188:191], v206, s[8:9] nt
	s_add_u32 s8, s8, 0x6000
	s_addc_u32 s9, s9, 0
	global_load_dwordx4 v[192:195], v206, s[8:9] nt
	s_add_u32 s8, s8, 0x6000
	s_addc_u32 s9, s9, 0
	global_load_dwordx4 v[196:199], v206, s[8:9] nt
	s_add_u32 s8, s8, 0x96000
	s_addc_u32 s9, s9, 0
	s_waitcnt vmcnt(27)
	v_mul_f32_e32 v212, 0xbfb8aa3b, v148
	v_mul_f32_e32 v213, 0xbfb8aa3b, v149
	v_mul_f32_e32 v248, 0xbfb8aa3b, v150
	v_mul_f32_e32 v249, 0xbfb8aa3b, v151
	v_exp_f32_e32 v212, v212
	v_exp_f32_e32 v213, v213
	v_exp_f32_e32 v248, v248
	v_exp_f32_e32 v249, v249
	v_add_f32_e32 v212, 1.0, v212
	v_add_f32_e32 v213, 1.0, v213
	v_add_f32_e32 v248, 1.0, v248
	v_add_f32_e32 v249, 1.0, v249
	v_rcp_f32_e32 v212, v212
	v_rcp_f32_e32 v213, v213
	v_rcp_f32_e32 v248, v248
	v_rcp_f32_e32 v249, v249
	v_mul_f32_e32 v148, v148, v212
	v_mul_f32_e32 v149, v149, v213
	v_mul_f32_e32 v150, v150, v248
	v_mul_f32_e32 v151, v151, v249
	s_waitcnt vmcnt(26)
	v_mul_f32_e32 v212, 0xbfb8aa3b, v152
	v_mul_f32_e32 v213, 0xbfb8aa3b, v153
	v_mul_f32_e32 v248, 0xbfb8aa3b, v154
	v_mul_f32_e32 v249, 0xbfb8aa3b, v155
	v_exp_f32_e32 v212, v212
	v_exp_f32_e32 v213, v213
	v_exp_f32_e32 v248, v248
	v_exp_f32_e32 v249, v249
	v_add_f32_e32 v212, 1.0, v212
	v_add_f32_e32 v213, 1.0, v213
	v_add_f32_e32 v248, 1.0, v248
	v_add_f32_e32 v249, 1.0, v249
	v_rcp_f32_e32 v212, v212
	v_rcp_f32_e32 v213, v213
	v_rcp_f32_e32 v248, v248
	v_rcp_f32_e32 v249, v249
	v_mul_f32_e32 v152, v152, v212
	v_mul_f32_e32 v153, v153, v213
	v_mul_f32_e32 v154, v154, v248
	v_mul_f32_e32 v155, v155, v249
	s_waitcnt vmcnt(25)
	v_mul_f32_e32 v212, 0xbfb8aa3b, v156
	v_mul_f32_e32 v213, 0xbfb8aa3b, v157
	v_mul_f32_e32 v248, 0xbfb8aa3b, v158
	v_mul_f32_e32 v249, 0xbfb8aa3b, v159
	v_exp_f32_e32 v212, v212
	v_exp_f32_e32 v213, v213
	v_exp_f32_e32 v248, v248
	v_exp_f32_e32 v249, v249
	v_add_f32_e32 v212, 1.0, v212
	v_add_f32_e32 v213, 1.0, v213
	v_add_f32_e32 v248, 1.0, v248
	v_add_f32_e32 v249, 1.0, v249
	v_rcp_f32_e32 v212, v212
	v_rcp_f32_e32 v213, v213
	v_rcp_f32_e32 v248, v248
	v_rcp_f32_e32 v249, v249
	v_mul_f32_e32 v156, v156, v212
	v_mul_f32_e32 v157, v157, v213
	v_mul_f32_e32 v158, v158, v248
	v_mul_f32_e32 v159, v159, v249
	s_waitcnt vmcnt(24)
	v_mul_f32_e32 v212, 0xbfb8aa3b, v160
	v_mul_f32_e32 v213, 0xbfb8aa3b, v161
	v_mul_f32_e32 v248, 0xbfb8aa3b, v162
	v_mul_f32_e32 v249, 0xbfb8aa3b, v163
	v_exp_f32_e32 v212, v212
	v_exp_f32_e32 v213, v213
	v_exp_f32_e32 v248, v248
	v_exp_f32_e32 v249, v249
	v_add_f32_e32 v212, 1.0, v212
	v_add_f32_e32 v213, 1.0, v213
	v_add_f32_e32 v248, 1.0, v248
	v_add_f32_e32 v249, 1.0, v249
	v_rcp_f32_e32 v212, v212
	v_rcp_f32_e32 v213, v213
	v_rcp_f32_e32 v248, v248
	v_rcp_f32_e32 v249, v249
	v_mul_f32_e32 v160, v160, v212
	v_mul_f32_e32 v161, v161, v213
	v_mul_f32_e32 v162, v162, v248
	v_mul_f32_e32 v163, v163, v249
	s_waitcnt vmcnt(23)
	v_mul_f32_e32 v212, 0xbfb8aa3b, v34
	v_mul_f32_e32 v213, 0xbfb8aa3b, v35
	v_mul_f32_e32 v248, 0xbfb8aa3b, v36
	v_mul_f32_e32 v249, 0xbfb8aa3b, v37
	v_exp_f32_e32 v212, v212
	v_exp_f32_e32 v213, v213
	v_exp_f32_e32 v248, v248
	v_exp_f32_e32 v249, v249
	v_add_f32_e32 v212, 1.0, v212
	v_add_f32_e32 v213, 1.0, v213
	v_add_f32_e32 v248, 1.0, v248
	v_add_f32_e32 v249, 1.0, v249
	v_rcp_f32_e32 v212, v212
	v_rcp_f32_e32 v213, v213
	v_rcp_f32_e32 v248, v248
	v_rcp_f32_e32 v249, v249
	v_mul_f32_e32 v34, v34, v212
	v_mul_f32_e32 v35, v35, v213
	v_mul_f32_e32 v36, v36, v248
	v_mul_f32_e32 v37, v37, v249
	s_waitcnt vmcnt(22)
; #define LAS __attribute__((address_space(3)))
; __device__ __forceinline__ void prologue_mod_item(const Args& a, LAS unsigned char* lds, int item, int tid) {
;     ...
;         for (int kk = 0; kk < 64; ++kk) { const int kl = kp * 64 + kk;
;             const float w = __builtin_nontemporal_load(&W[(size_t)(half * 512 + kl) * (6 * DM) + n0 + col]);
;             const LAS f32x4* sp = (const LAS f32x4*)(sl + kl * NSEQ);
; #pragma unroll
;             for (int q = 0; q < NSEQ / 4; ++q) { const f32x4 sv = sp[q]; const f32x2 w2 = (f32x2){w, w};
;                 acc[2 * q] = __builtin_elementwise_fma((f32x2){sv[0], sv[1]}, w2, acc[2 * q]); acc[2 * q + 1] = __builtin_elementwise_fma((f32x2){sv[2], sv[3]}, w2, acc[2 * q + 1]); } }
	v_mul_f32_e32 v212, 0xbfb8aa3b, v38
	v_mul_f32_e32 v213, 0xbfb8aa3b, v39
	v_mul_f32_e32 v248, 0xbfb8aa3b, v40
	v_mul_f32_e32 v249, 0xbfb8aa3b, v41
	v_exp_f32_e32 v212, v212
	v_exp_f32_e32 v213, v213
	v_exp_f32_e32 v248, v248
	v_exp_f32_e32 v249, v249
	v_add_f32_e32 v212, 1.0, v212
	v_add_f32_e32 v213, 1.0, v213
	v_add_f32_e32 v248, 1.0, v248
	v_add_f32_e32 v249, 1.0, v249
	v_rcp_f32_e32 v212, v212
	v_rcp_f32_e32 v213, v213
	v_rcp_f32_e32 v248, v248
	v_rcp_f32_e32 v249, v249
	v_mul_f32_e32 v38, v38, v212
	v_mul_f32_e32 v39, v39, v213
	v_mul_f32_e32 v40, v40, v248
	v_mul_f32_e32 v41, v41, v249
	s_waitcnt vmcnt(21)
	v_mfma_f32_16x16x4_f32 v[62:65], v148, v216, v[62:65]
	v_mfma_f32_16x16x4_f32 v[66:69], v148, v217, v[66:69]
	v_mfma_f32_16x16x4_f32 v[70:73], v148, v218, v[70:73]
	v_mfma_f32_16x16x4_f32 v[74:77], v148, v219, v[74:77]
	v_mfma_f32_16x16x4_f32 v[78:81], v156, v216, v[78:81]
	v_mfma_f32_16x16x4_f32 v[82:85], v156, v217, v[82:85]
	v_mfma_f32_16x16x4_f32 v[86:89], v156, v218, v[86:89]
	v_mfma_f32_16x16x4_f32 v[90:93], v156, v219, v[90:93]
	v_mfma_f32_16x16x4_f32 v[98:101], v34, v216, v[98:101]
	v_mfma_f32_16x16x4_f32 v[102:105], v34, v217, v[102:105]
	v_mfma_f32_16x16x4_f32 v[106:109], v34, v218, v[106:109]
	v_mfma_f32_16x16x4_f32 v[110:113], v34, v219, v[110:113]
	s_waitcnt vmcnt(20)
	v_mfma_f32_16x16x4_f32 v[62:65], v149, v220, v[62:65]
	v_mfma_f32_16x16x4_f32 v[66:69], v149, v221, v[66:69]
	v_mfma_f32_16x16x4_f32 v[70:73], v149, v222, v[70:73]
	v_mfma_f32_16x16x4_f32 v[74:77], v149, v223, v[74:77]
	v_mfma_f32_16x16x4_f32 v[78:81], v157, v220, v[78:81]
	v_mfma_f32_16x16x4_f32 v[82:85], v157, v221, v[82:85]
	v_mfma_f32_16x16x4_f32 v[86:89], v157, v222, v[86:89]
	v_mfma_f32_16x16x4_f32 v[90:93], v157, v223, v[90:93]
	v_mfma_f32_16x16x4_f32 v[98:101], v35, v220, v[98:101]
	v_mfma_f32_16x16x4_f32 v[102:105], v35, v221, v[102:105]
	v_mfma_f32_16x16x4_f32 v[106:109], v35, v222, v[106:109]
	v_mfma_f32_16x16x4_f32 v[110:113], v35, v223, v[110:113]
	s_waitcnt vmcnt(19)
	v_mfma_f32_16x16x4_f32 v[62:65], v150, v224, v[62:65]
	v_mfma_f32_16x16x4_f32 v[66:69], v150, v225, v[66:69]
	v_mfma_f32_16x16x4_f32 v[70:73], v150, v226, v[70:73]
	v_mfma_f32_16x16x4_f32 v[74:77], v150, v227, v[74:77]
	v_mfma_f32_16x16x4_f32 v[78:81], v158, v224, v[78:81]
	v_mfma_f32_16x16x4_f32 v[82:85], v158, v225, v[82:85]
	v_mfma_f32_16x16x4_f32 v[86:89], v158, v226, v[86:89]
	v_mfma_f32_16x16x4_f32 v[90:93], v158, v227, v[90:93]
	v_mfma_f32_16x16x4_f32 v[98:101], v36, v224, v[98:101]
	v_mfma_f32_16x16x4_f32 v[102:105], v36, v225, v[102:105]
	v_mfma_f32_16x16x4_f32 v[106:109], v36, v226, v[106:109]
	v_mfma_f32_16x16x4_f32 v[110:113], v36, v227, v[110:113]
	s_waitcnt vmcnt(18)
	v_mfma_f32_16x16x4_f32 v[62:65], v151, v228, v[62:65]
	v_mfma_f32_16x16x4_f32 v[66:69], v151, v229, v[66:69]
	v_mfma_f32_16x16x4_f32 v[70:73], v151, v230, v[70:73]
	v_mfma_f32_16x16x4_f32 v[74:77], v151, v231, v[74:77]
	v_mfma_f32_16x16x4_f32 v[78:81], v159, v228, v[78:81]
	v_mfma_f32_16x16x4_f32 v[82:85], v159, v229, v[82:85]
	v_mfma_f32_16x16x4_f32 v[86:89], v159, v230, v[86:89]
	v_mfma_f32_16x16x4_f32 v[90:93], v159, v231, v[90:93]
	v_mfma_f32_16x16x4_f32 v[98:101], v37, v228, v[98:101]
	v_mfma_f32_16x16x4_f32 v[102:105], v37, v229, v[102:105]
	v_mfma_f32_16x16x4_f32 v[106:109], v37, v230, v[106:109]
	v_mfma_f32_16x16x4_f32 v[110:113], v37, v231, v[110:113]
	s_waitcnt vmcnt(17)
	v_mfma_f32_16x16x4_f32 v[62:65], v152, v232, v[62:65]
	v_mfma_f32_16x16x4_f32 v[66:69], v152, v233, v[66:69]
	v_mfma_f32_16x16x4_f32 v[70:73], v152, v234, v[70:73]
	v_mfma_f32_16x16x4_f32 v[74:77], v152, v235, v[74:77]
	v_mfma_f32_16x16x4_f32 v[78:81], v160, v232, v[78:81]
	v_mfma_f32_16x16x4_f32 v[82:85], v160, v233, v[82:85]
	v_mfma_f32_16x16x4_f32 v[86:89], v160, v234, v[86:89]
	v_mfma_f32_16x16x4_f32 v[90:93], v160, v235, v[90:93]
	v_mfma_f32_16x16x4_f32 v[98:101], v38, v232, v[98:101]
	v_mfma_f32_16x16x4_f32 v[102:105], v38, v233, v[102:105]
	v_mfma_f32_16x16x4_f32 v[106:109], v38, v234, v[106:109]
	v_mfma_f32_16x16x4_f32 v[110:113], v38, v235, v[110:113]
	s_waitcnt vmcnt(16)
	v_mfma_f32_16x16x4_f32 v[62:65], v153, v236, v[62:65]
	v_mfma_f32_16x16x4_f32 v[66:69], v153, v237, v[66:69]
	v_mfma_f32_16x16x4_f32 v[70:73], v153, v238, v[70:73]
	v_mfma_f32_16x16x4_f32 v[74:77], v153, v239, v[74:77]
	v_mfma_f32_16x16x4_f32 v[78:81], v161, v236, v[78:81]
	v_mfma_f32_16x16x4_f32 v[82:85], v161, v237, v[82:85]
	v_mfma_f32_16x16x4_f32 v[86:89], v161, v238, v[86:89]
	v_mfma_f32_16x16x4_f32 v[90:93], v161, v239, v[90:93]
	v_mfma_f32_16x16x4_f32 v[98:101], v39, v236, v[98:101]
	v_mfma_f32_16x16x4_f32 v[102:105], v39, v237, v[102:105]
	v_mfma_f32_16x16x4_f32 v[106:109], v39, v238, v[106:109]
	v_mfma_f32_16x16x4_f32 v[110:113], v39, v239, v[110:113]
	s_waitcnt vmcnt(15)
	v_mfma_f32_16x16x4_f32 v[62:65], v154, v240, v[62:65]
	v_mfma_f32_16x16x4_f32 v[66:69], v154, v241, v[66:69]
	v_mfma_f32_16x16x4_f32 v[70:73], v154, v242, v[70:73]
	v_mfma_f32_16x16x4_f32 v[74:77], v154, v243, v[74:77]
	v_mfma_f32_16x16x4_f32 v[78:81], v162, v240, v[78:81]
	v_mfma_f32_16x16x4_f32 v[82:85], v162, v241, v[82:85]
	v_mfma_f32_16x16x4_f32 v[86:89], v162, v242, v[86:89]
	v_mfma_f32_16x16x4_f32 v[90:93], v162, v243, v[90:93]
	v_mfma_f32_16x16x4_f32 v[98:101], v40, v240, v[98:101]
	v_mfma_f32_16x16x4_f32 v[102:105], v40, v241, v[102:105]
	v_mfma_f32_16x16x4_f32 v[106:109], v40, v242, v[106:109]
	v_mfma_f32_16x16x4_f32 v[110:113], v40, v243, v[110:113]
	s_waitcnt vmcnt(14)
; #define LAS __attribute__((address_space(3)))
; __device__ __forceinline__ void prologue_mod_item(const Args& a, LAS unsigned char* lds, int item, int tid) {
;     ...
;         for (int kk = 0; kk < 64; ++kk) { const int kl = kp * 64 + kk;
;             const float w = __builtin_nontemporal_load(&W[(size_t)(half * 512 + kl) * (6 * DM) + n0 + col]);
;             const LAS f32x4* sp = (const LAS f32x4*)(sl + kl * NSEQ);
; #pragma unroll
;             for (int q = 0; q < NSEQ / 4; ++q) { const f32x4 sv = sp[q]; const f32x2 w2 = (f32x2){w, w};
;                 acc[2 * q] = __builtin_elementwise_fma((f32x2){sv[0], sv[1]}, w2, acc[2 * q]); acc[2 * q + 1] = __builtin_elementwise_fma((f32x2){sv[2], sv[3]}, w2, acc[2 * q + 1]); } }
	v_mfma_f32_16x16x4_f32 v[62:65], v155, v244, v[62:65]
	v_mfma_f32_16x16x4_f32 v[66:69], v155, v245, v[66:69]
	v_mfma_f32_16x16x4_f32 v[70:73], v155, v246, v[70:73]
	v_mfma_f32_16x16x4_f32 v[74:77], v155, v247, v[74:77]
	v_mfma_f32_16x16x4_f32 v[78:81], v163, v244, v[78:81]
	v_mfma_f32_16x16x4_f32 v[82:85], v163, v245, v[82:85]
	v_mfma_f32_16x16x4_f32 v[86:89], v163, v246, v[86:89]
	v_mfma_f32_16x16x4_f32 v[90:93], v163, v247, v[90:93]
	v_mfma_f32_16x16x4_f32 v[98:101], v41, v244, v[98:101]
	v_mfma_f32_16x16x4_f32 v[102:105], v41, v245, v[102:105]
	v_mfma_f32_16x16x4_f32 v[106:109], v41, v246, v[106:109]
	v_mfma_f32_16x16x4_f32 v[110:113], v41, v247, v[110:113]
	global_load_dwordx4 v[148:151], v204, s[0:1] offset:384
	global_load_dwordx4 v[152:155], v204, s[0:1] offset:400
	global_load_dwordx4 v[156:159], v204, s[18:19] offset:384
	global_load_dwordx4 v[160:163], v204, s[18:19] offset:400
	global_load_dwordx4 v[34:37], v205, s[18:19] offset:384
	global_load_dwordx4 v[38:41], v205, s[18:19] offset:400
	global_load_dwordx4 v[216:219], v206, s[8:9] nt
	s_add_u32 s8, s8, 0x6000
	s_addc_u32 s9, s9, 0
	global_load_dwordx4 v[220:223], v206, s[8:9] nt
	s_add_u32 s8, s8, 0x6000
	s_addc_u32 s9, s9, 0
	global_load_dwordx4 v[224:227], v206, s[8:9] nt
	s_add_u32 s8, s8, 0x6000
	s_addc_u32 s9, s9, 0
	global_load_dwordx4 v[228:231], v206, s[8:9] nt
	s_add_u32 s8, s8, 0x6000
	s_addc_u32 s9, s9, 0
	global_load_dwordx4 v[232:235], v206, s[8:9] nt
	s_add_u32 s8, s8, 0x6000
	s_addc_u32 s9, s9, 0
	global_load_dwordx4 v[236:239], v206, s[8:9] nt
	s_add_u32 s8, s8, 0x6000
	s_addc_u32 s9, s9, 0
	global_load_dwordx4 v[240:243], v206, s[8:9] nt
	s_add_u32 s8, s8, 0x6000
	s_addc_u32 s9, s9, 0
	global_load_dwordx4 v[244:247], v206, s[8:9] nt
	s_add_u32 s8, s8, 0x96000
	s_addc_u32 s9, s9, 0
	s_waitcnt vmcnt(27)
	v_mul_f32_e32 v212, 0xbfb8aa3b, v120
	v_mul_f32_e32 v213, 0xbfb8aa3b, v121
	v_mul_f32_e32 v248, 0xbfb8aa3b, v122
	v_mul_f32_e32 v249, 0xbfb8aa3b, v123
	v_exp_f32_e32 v212, v212
	v_exp_f32_e32 v213, v213
	v_exp_f32_e32 v248, v248
	v_exp_f32_e32 v249, v249
	v_add_f32_e32 v212, 1.0, v212
	v_add_f32_e32 v213, 1.0, v213
	v_add_f32_e32 v248, 1.0, v248
	v_add_f32_e32 v249, 1.0, v249
	v_rcp_f32_e32 v212, v212
	v_rcp_f32_e32 v213, v213
	v_rcp_f32_e32 v248, v248
	v_rcp_f32_e32 v249, v249
	v_mul_f32_e32 v120, v120, v212
	v_mul_f32_e32 v121, v121, v213
	v_mul_f32_e32 v122, v122, v248
	v_mul_f32_e32 v123, v123, v249
	s_waitcnt vmcnt(26)
	v_mul_f32_e32 v212, 0xbfb8aa3b, v124
	v_mul_f32_e32 v213, 0xbfb8aa3b, v125
	v_mul_f32_e32 v248, 0xbfb8aa3b, v126
	v_mul_f32_e32 v249, 0xbfb8aa3b, v127
	v_exp_f32_e32 v212, v212
	v_exp_f32_e32 v213, v213
	v_exp_f32_e32 v248, v248
	v_exp_f32_e32 v249, v249
	v_add_f32_e32 v212, 1.0, v212
	v_add_f32_e32 v213, 1.0, v213
	v_add_f32_e32 v248, 1.0, v248
	v_add_f32_e32 v249, 1.0, v249
	v_rcp_f32_e32 v212, v212
	v_rcp_f32_e32 v213, v213
	v_rcp_f32_e32 v248, v248
	v_rcp_f32_e32 v249, v249
	v_mul_f32_e32 v124, v124, v212
	v_mul_f32_e32 v125, v125, v213
	v_mul_f32_e32 v126, v126, v248
	v_mul_f32_e32 v127, v127, v249
	s_waitcnt vmcnt(25)
	v_mul_f32_e32 v212, 0xbfb8aa3b, v128
	v_mul_f32_e32 v213, 0xbfb8aa3b, v129
	v_mul_f32_e32 v248, 0xbfb8aa3b, v130
	v_mul_f32_e32 v249, 0xbfb8aa3b, v131
	v_exp_f32_e32 v212, v212
	v_exp_f32_e32 v213, v213
	v_exp_f32_e32 v248, v248
	v_exp_f32_e32 v249, v249
	v_add_f32_e32 v212, 1.0, v212
	v_add_f32_e32 v213, 1.0, v213
	v_add_f32_e32 v248, 1.0, v248
	v_add_f32_e32 v249, 1.0, v249
	v_rcp_f32_e32 v212, v212
	v_rcp_f32_e32 v213, v213
	v_rcp_f32_e32 v248, v248
	v_rcp_f32_e32 v249, v249
	v_mul_f32_e32 v128, v128, v212
	v_mul_f32_e32 v129, v129, v213
	v_mul_f32_e32 v130, v130, v248
	v_mul_f32_e32 v131, v131, v249
	s_waitcnt vmcnt(24)
	v_mul_f32_e32 v212, 0xbfb8aa3b, v132
	v_mul_f32_e32 v213, 0xbfb8aa3b, v133
	v_mul_f32_e32 v248, 0xbfb8aa3b, v134
	v_mul_f32_e32 v249, 0xbfb8aa3b, v135
	v_exp_f32_e32 v212, v212
	v_exp_f32_e32 v213, v213
	v_exp_f32_e32 v248, v248
	v_exp_f32_e32 v249, v249
	v_add_f32_e32 v212, 1.0, v212
	v_add_f32_e32 v213, 1.0, v213
	v_add_f32_e32 v248, 1.0, v248
	v_add_f32_e32 v249, 1.0, v249
	v_rcp_f32_e32 v212, v212
	v_rcp_f32_e32 v213, v213
	v_rcp_f32_e32 v248, v248
	v_rcp_f32_e32 v249, v249
	v_mul_f32_e32 v132, v132, v212
	v_mul_f32_e32 v133, v133, v213
	v_mul_f32_e32 v134, v134, v248
	v_mul_f32_e32 v135, v135, v249
	s_waitcnt vmcnt(23)
	v_mul_f32_e32 v212, 0xbfb8aa3b, v136
	v_mul_f32_e32 v213, 0xbfb8aa3b, v137
	v_mul_f32_e32 v248, 0xbfb8aa3b, v138
	v_mul_f32_e32 v249, 0xbfb8aa3b, v139
	v_exp_f32_e32 v212, v212
	v_exp_f32_e32 v213, v213
	v_exp_f32_e32 v248, v248
	v_exp_f32_e32 v249, v249
	v_add_f32_e32 v212, 1.0, v212
	v_add_f32_e32 v213, 1.0, v213
	v_add_f32_e32 v248, 1.0, v248
	v_add_f32_e32 v249, 1.0, v249
	v_rcp_f32_e32 v212, v212
	v_rcp_f32_e32 v213, v213
	v_rcp_f32_e32 v248, v248
	v_rcp_f32_e32 v249, v249
	v_mul_f32_e32 v136, v136, v212
	v_mul_f32_e32 v137, v137, v213
	v_mul_f32_e32 v138, v138, v248
	v_mul_f32_e32 v139, v139, v249
	s_waitcnt vmcnt(22)
	v_mul_f32_e32 v212, 0xbfb8aa3b, v140
	v_mul_f32_e32 v213, 0xbfb8aa3b, v141
	v_mul_f32_e32 v248, 0xbfb8aa3b, v142
	v_mul_f32_e32 v249, 0xbfb8aa3b, v143
	v_exp_f32_e32 v212, v212
	v_exp_f32_e32 v213, v213
	v_exp_f32_e32 v248, v248
	v_exp_f32_e32 v249, v249
	v_add_f32_e32 v212, 1.0, v212
	v_add_f32_e32 v213, 1.0, v213
	v_add_f32_e32 v248, 1.0, v248
	v_add_f32_e32 v249, 1.0, v249
	v_rcp_f32_e32 v212, v212
	v_rcp_f32_e32 v213, v213
	v_rcp_f32_e32 v248, v248
	v_rcp_f32_e32 v249, v249
	v_mul_f32_e32 v140, v140, v212
	v_mul_f32_e32 v141, v141, v213
	v_mul_f32_e32 v142, v142, v248
	v_mul_f32_e32 v143, v143, v249
	s_waitcnt vmcnt(21)
; #define LAS __attribute__((address_space(3)))
; __device__ __forceinline__ void prologue_mod_item(const Args& a, LAS unsigned char* lds, int item, int tid) {
;     ...
;         for (int kk = 0; kk < 64; ++kk) { const int kl = kp * 64 + kk;
;             const float w = __builtin_nontemporal_load(&W[(size_t)(half * 512 + kl) * (6 * DM) + n0 + col]);
;             const LAS f32x4* sp = (const LAS f32x4*)(sl + kl * NSEQ);
; #pragma unroll
;             for (int q = 0; q < NSEQ / 4; ++q) { const f32x4 sv = sp[q]; const f32x2 w2 = (f32x2){w, w};
;                 acc[2 * q] = __builtin_elementwise_fma((f32x2){sv[0], sv[1]}, w2, acc[2 * q]); acc[2 * q + 1] = __builtin_elementwise_fma((f32x2){sv[2], sv[3]}, w2, acc[2 * q + 1]); } }
	v_mfma_f32_16x16x4_f32 v[62:65], v120, v168, v[62:65]
	v_mfma_f32_16x16x4_f32 v[66:69], v120, v169, v[66:69]
	v_mfma_f32_16x16x4_f32 v[70:73], v120, v170, v[70:73]
	v_mfma_f32_16x16x4_f32 v[74:77], v120, v171, v[74:77]
	v_mfma_f32_16x16x4_f32 v[78:81], v128, v168, v[78:81]
	v_mfma_f32_16x16x4_f32 v[82:85], v128, v169, v[82:85]
	v_mfma_f32_16x16x4_f32 v[86:89], v128, v170, v[86:89]
	v_mfma_f32_16x16x4_f32 v[90:93], v128, v171, v[90:93]
	v_mfma_f32_16x16x4_f32 v[98:101], v136, v168, v[98:101]
	v_mfma_f32_16x16x4_f32 v[102:105], v136, v169, v[102:105]
	v_mfma_f32_16x16x4_f32 v[106:109], v136, v170, v[106:109]
	v_mfma_f32_16x16x4_f32 v[110:113], v136, v171, v[110:113]
	s_waitcnt vmcnt(20)
	v_mfma_f32_16x16x4_f32 v[62:65], v121, v172, v[62:65]
	v_mfma_f32_16x16x4_f32 v[66:69], v121, v173, v[66:69]
	v_mfma_f32_16x16x4_f32 v[70:73], v121, v174, v[70:73]
	v_mfma_f32_16x16x4_f32 v[74:77], v121, v175, v[74:77]
	v_mfma_f32_16x16x4_f32 v[78:81], v129, v172, v[78:81]
	v_mfma_f32_16x16x4_f32 v[82:85], v129, v173, v[82:85]
	v_mfma_f32_16x16x4_f32 v[86:89], v129, v174, v[86:89]
	v_mfma_f32_16x16x4_f32 v[90:93], v129, v175, v[90:93]
	v_mfma_f32_16x16x4_f32 v[98:101], v137, v172, v[98:101]
	v_mfma_f32_16x16x4_f32 v[102:105], v137, v173, v[102:105]
	v_mfma_f32_16x16x4_f32 v[106:109], v137, v174, v[106:109]
	v_mfma_f32_16x16x4_f32 v[110:113], v137, v175, v[110:113]
	s_waitcnt vmcnt(19)
	v_mfma_f32_16x16x4_f32 v[62:65], v122, v176, v[62:65]
	v_mfma_f32_16x16x4_f32 v[66:69], v122, v177, v[66:69]
	v_mfma_f32_16x16x4_f32 v[70:73], v122, v178, v[70:73]
	v_mfma_f32_16x16x4_f32 v[74:77], v122, v179, v[74:77]
	v_mfma_f32_16x16x4_f32 v[78:81], v130, v176, v[78:81]
	v_mfma_f32_16x16x4_f32 v[82:85], v130, v177, v[82:85]
	v_mfma_f32_16x16x4_f32 v[86:89], v130, v178, v[86:89]
	v_mfma_f32_16x16x4_f32 v[90:93], v130, v179, v[90:93]
	v_mfma_f32_16x16x4_f32 v[98:101], v138, v176, v[98:101]
	v_mfma_f32_16x16x4_f32 v[102:105], v138, v177, v[102:105]
	v_mfma_f32_16x16x4_f32 v[106:109], v138, v178, v[106:109]
	v_mfma_f32_16x16x4_f32 v[110:113], v138, v179, v[110:113]
	s_waitcnt vmcnt(18)
	v_mfma_f32_16x16x4_f32 v[62:65], v123, v180, v[62:65]
	v_mfma_f32_16x16x4_f32 v[66:69], v123, v181, v[66:69]
	v_mfma_f32_16x16x4_f32 v[70:73], v123, v182, v[70:73]
	v_mfma_f32_16x16x4_f32 v[74:77], v123, v183, v[74:77]
	v_mfma_f32_16x16x4_f32 v[78:81], v131, v180, v[78:81]
	v_mfma_f32_16x16x4_f32 v[82:85], v131, v181, v[82:85]
	v_mfma_f32_16x16x4_f32 v[86:89], v131, v182, v[86:89]
	v_mfma_f32_16x16x4_f32 v[90:93], v131, v183, v[90:93]
	v_mfma_f32_16x16x4_f32 v[98:101], v139, v180, v[98:101]
	v_mfma_f32_16x16x4_f32 v[102:105], v139, v181, v[102:105]
	v_mfma_f32_16x16x4_f32 v[106:109], v139, v182, v[106:109]
	v_mfma_f32_16x16x4_f32 v[110:113], v139, v183, v[110:113]
	s_waitcnt vmcnt(17)
	v_mfma_f32_16x16x4_f32 v[62:65], v124, v184, v[62:65]
	v_mfma_f32_16x16x4_f32 v[66:69], v124, v185, v[66:69]
	v_mfma_f32_16x16x4_f32 v[70:73], v124, v186, v[70:73]
	v_mfma_f32_16x16x4_f32 v[74:77], v124, v187, v[74:77]
	v_mfma_f32_16x16x4_f32 v[78:81], v132, v184, v[78:81]
	v_mfma_f32_16x16x4_f32 v[82:85], v132, v185, v[82:85]
	v_mfma_f32_16x16x4_f32 v[86:89], v132, v186, v[86:89]
	v_mfma_f32_16x16x4_f32 v[90:93], v132, v187, v[90:93]
	v_mfma_f32_16x16x4_f32 v[98:101], v140, v184, v[98:101]
	v_mfma_f32_16x16x4_f32 v[102:105], v140, v185, v[102:105]
	v_mfma_f32_16x16x4_f32 v[106:109], v140, v186, v[106:109]
	v_mfma_f32_16x16x4_f32 v[110:113], v140, v187, v[110:113]
	s_waitcnt vmcnt(16)
	v_mfma_f32_16x16x4_f32 v[62:65], v125, v188, v[62:65]
	v_mfma_f32_16x16x4_f32 v[66:69], v125, v189, v[66:69]
	v_mfma_f32_16x16x4_f32 v[70:73], v125, v190, v[70:73]
	v_mfma_f32_16x16x4_f32 v[74:77], v125, v191, v[74:77]
	v_mfma_f32_16x16x4_f32 v[78:81], v133, v188, v[78:81]
	v_mfma_f32_16x16x4_f32 v[82:85], v133, v189, v[82:85]
	v_mfma_f32_16x16x4_f32 v[86:89], v133, v190, v[86:89]
	v_mfma_f32_16x16x4_f32 v[90:93], v133, v191, v[90:93]
	v_mfma_f32_16x16x4_f32 v[98:101], v141, v188, v[98:101]
	v_mfma_f32_16x16x4_f32 v[102:105], v141, v189, v[102:105]
	v_mfma_f32_16x16x4_f32 v[106:109], v141, v190, v[106:109]
	v_mfma_f32_16x16x4_f32 v[110:113], v141, v191, v[110:113]
	s_waitcnt vmcnt(15)
	v_mfma_f32_16x16x4_f32 v[62:65], v126, v192, v[62:65]
	v_mfma_f32_16x16x4_f32 v[66:69], v126, v193, v[66:69]
	v_mfma_f32_16x16x4_f32 v[70:73], v126, v194, v[70:73]
	v_mfma_f32_16x16x4_f32 v[74:77], v126, v195, v[74:77]
	v_mfma_f32_16x16x4_f32 v[78:81], v134, v192, v[78:81]
	v_mfma_f32_16x16x4_f32 v[82:85], v134, v193, v[82:85]
	v_mfma_f32_16x16x4_f32 v[86:89], v134, v194, v[86:89]
	v_mfma_f32_16x16x4_f32 v[90:93], v134, v195, v[90:93]
	v_mfma_f32_16x16x4_f32 v[98:101], v142, v192, v[98:101]
	v_mfma_f32_16x16x4_f32 v[102:105], v142, v193, v[102:105]
	v_mfma_f32_16x16x4_f32 v[106:109], v142, v194, v[106:109]
	v_mfma_f32_16x16x4_f32 v[110:113], v142, v195, v[110:113]
	s_waitcnt vmcnt(14)
	v_mfma_f32_16x16x4_f32 v[62:65], v127, v196, v[62:65]
	v_mfma_f32_16x16x4_f32 v[66:69], v127, v197, v[66:69]
	v_mfma_f32_16x16x4_f32 v[70:73], v127, v198, v[70:73]
	v_mfma_f32_16x16x4_f32 v[74:77], v127, v199, v[74:77]
	v_mfma_f32_16x16x4_f32 v[78:81], v135, v196, v[78:81]
	v_mfma_f32_16x16x4_f32 v[82:85], v135, v197, v[82:85]
	v_mfma_f32_16x16x4_f32 v[86:89], v135, v198, v[86:89]
	v_mfma_f32_16x16x4_f32 v[90:93], v135, v199, v[90:93]
	v_mfma_f32_16x16x4_f32 v[98:101], v143, v196, v[98:101]
	v_mfma_f32_16x16x4_f32 v[102:105], v143, v197, v[102:105]
	v_mfma_f32_16x16x4_f32 v[106:109], v143, v198, v[106:109]
	v_mfma_f32_16x16x4_f32 v[110:113], v143, v199, v[110:113]
	s_waitcnt vmcnt(13)
; #define LAS __attribute__((address_space(3)))
; __device__ __forceinline__ void prologue_mod_item(const Args& a, LAS unsigned char* lds, int item, int tid) {
;     ...
;         for (int kk = 0; kk < 64; ++kk) { const int kl = kp * 64 + kk;
;             const float w = __builtin_nontemporal_load(&W[(size_t)(half * 512 + kl) * (6 * DM) + n0 + col]);
;             const LAS f32x4* sp = (const LAS f32x4*)(sl + kl * NSEQ);
; #pragma unroll
;             for (int q = 0; q < NSEQ / 4; ++q) { const f32x4 sv = sp[q]; const f32x2 w2 = (f32x2){w, w};
;                 acc[2 * q] = __builtin_elementwise_fma((f32x2){sv[0], sv[1]}, w2, acc[2 * q]); acc[2 * q + 1] = __builtin_elementwise_fma((f32x2){sv[2], sv[3]}, w2, acc[2 * q + 1]); } }
	v_mul_f32_e32 v212, 0xbfb8aa3b, v148
	v_mul_f32_e32 v213, 0xbfb8aa3b, v149
	v_mul_f32_e32 v248, 0xbfb8aa3b, v150
	v_mul_f32_e32 v249, 0xbfb8aa3b, v151
	v_exp_f32_e32 v212, v212
	v_exp_f32_e32 v213, v213
	v_exp_f32_e32 v248, v248
	v_exp_f32_e32 v249, v249
	v_add_f32_e32 v212, 1.0, v212
	v_add_f32_e32 v213, 1.0, v213
	v_add_f32_e32 v248, 1.0, v248
	v_add_f32_e32 v249, 1.0, v249
	v_rcp_f32_e32 v212, v212
	v_rcp_f32_e32 v213, v213
	v_rcp_f32_e32 v248, v248
	v_rcp_f32_e32 v249, v249
	v_mul_f32_e32 v148, v148, v212
	v_mul_f32_e32 v149, v149, v213
	v_mul_f32_e32 v150, v150, v248
	v_mul_f32_e32 v151, v151, v249
	s_waitcnt vmcnt(12)
	v_mul_f32_e32 v212, 0xbfb8aa3b, v152
	v_mul_f32_e32 v213, 0xbfb8aa3b, v153
	v_mul_f32_e32 v248, 0xbfb8aa3b, v154
	v_mul_f32_e32 v249, 0xbfb8aa3b, v155
	v_exp_f32_e32 v212, v212
	v_exp_f32_e32 v213, v213
	v_exp_f32_e32 v248, v248
	v_exp_f32_e32 v249, v249
	v_add_f32_e32 v212, 1.0, v212
	v_add_f32_e32 v213, 1.0, v213
	v_add_f32_e32 v248, 1.0, v248
	v_add_f32_e32 v249, 1.0, v249
	v_rcp_f32_e32 v212, v212
	v_rcp_f32_e32 v213, v213
	v_rcp_f32_e32 v248, v248
	v_rcp_f32_e32 v249, v249
	v_mul_f32_e32 v152, v152, v212
	v_mul_f32_e32 v153, v153, v213
	v_mul_f32_e32 v154, v154, v248
	v_mul_f32_e32 v155, v155, v249
	s_waitcnt vmcnt(11)
	v_mul_f32_e32 v212, 0xbfb8aa3b, v156
	v_mul_f32_e32 v213, 0xbfb8aa3b, v157
	v_mul_f32_e32 v248, 0xbfb8aa3b, v158
	v_mul_f32_e32 v249, 0xbfb8aa3b, v159
	v_exp_f32_e32 v212, v212
	v_exp_f32_e32 v213, v213
	v_exp_f32_e32 v248, v248
	v_exp_f32_e32 v249, v249
	v_add_f32_e32 v212, 1.0, v212
	v_add_f32_e32 v213, 1.0, v213
	v_add_f32_e32 v248, 1.0, v248
	v_add_f32_e32 v249, 1.0, v249
	v_rcp_f32_e32 v212, v212
	v_rcp_f32_e32 v213, v213
	v_rcp_f32_e32 v248, v248
	v_rcp_f32_e32 v249, v249
	v_mul_f32_e32 v156, v156, v212
	v_mul_f32_e32 v157, v157, v213
	v_mul_f32_e32 v158, v158, v248
	v_mul_f32_e32 v159, v159, v249
	s_waitcnt vmcnt(10)
	v_mul_f32_e32 v212, 0xbfb8aa3b, v160
	v_mul_f32_e32 v213, 0xbfb8aa3b, v161
	v_mul_f32_e32 v248, 0xbfb8aa3b, v162
	v_mul_f32_e32 v249, 0xbfb8aa3b, v163
	v_exp_f32_e32 v212, v212
	v_exp_f32_e32 v213, v213
	v_exp_f32_e32 v248, v248
	v_exp_f32_e32 v249, v249
	v_add_f32_e32 v212, 1.0, v212
	v_add_f32_e32 v213, 1.0, v213
	v_add_f32_e32 v248, 1.0, v248
	v_add_f32_e32 v249, 1.0, v249
	v_rcp_f32_e32 v212, v212
	v_rcp_f32_e32 v213, v213
	v_rcp_f32_e32 v248, v248
	v_rcp_f32_e32 v249, v249
	v_mul_f32_e32 v160, v160, v212
	v_mul_f32_e32 v161, v161, v213
	v_mul_f32_e32 v162, v162, v248
	v_mul_f32_e32 v163, v163, v249
	s_waitcnt vmcnt(9)
	v_mul_f32_e32 v212, 0xbfb8aa3b, v34
	v_mul_f32_e32 v213, 0xbfb8aa3b, v35
	v_mul_f32_e32 v248, 0xbfb8aa3b, v36
	v_mul_f32_e32 v249, 0xbfb8aa3b, v37
	v_exp_f32_e32 v212, v212
	v_exp_f32_e32 v213, v213
	v_exp_f32_e32 v248, v248
	v_exp_f32_e32 v249, v249
	v_add_f32_e32 v212, 1.0, v212
	v_add_f32_e32 v213, 1.0, v213
	v_add_f32_e32 v248, 1.0, v248
	v_add_f32_e32 v249, 1.0, v249
	v_rcp_f32_e32 v212, v212
	v_rcp_f32_e32 v213, v213
	v_rcp_f32_e32 v248, v248
	v_rcp_f32_e32 v249, v249
	v_mul_f32_e32 v34, v34, v212
	v_mul_f32_e32 v35, v35, v213
	v_mul_f32_e32 v36, v36, v248
	v_mul_f32_e32 v37, v37, v249
	s_waitcnt vmcnt(8)
	v_mul_f32_e32 v212, 0xbfb8aa3b, v38
	v_mul_f32_e32 v213, 0xbfb8aa3b, v39
	v_mul_f32_e32 v248, 0xbfb8aa3b, v40
	v_mul_f32_e32 v249, 0xbfb8aa3b, v41
	v_exp_f32_e32 v212, v212
	v_exp_f32_e32 v213, v213
	v_exp_f32_e32 v248, v248
	v_exp_f32_e32 v249, v249
	v_add_f32_e32 v212, 1.0, v212
	v_add_f32_e32 v213, 1.0, v213
	v_add_f32_e32 v248, 1.0, v248
	v_add_f32_e32 v249, 1.0, v249
	v_rcp_f32_e32 v212, v212
	v_rcp_f32_e32 v213, v213
	v_rcp_f32_e32 v248, v248
	v_rcp_f32_e32 v249, v249
	v_mul_f32_e32 v38, v38, v212
	v_mul_f32_e32 v39, v39, v213
	v_mul_f32_e32 v40, v40, v248
	v_mul_f32_e32 v41, v41, v249
	s_waitcnt vmcnt(7)
	v_mfma_f32_16x16x4_f32 v[62:65], v148, v216, v[62:65]
	v_mfma_f32_16x16x4_f32 v[66:69], v148, v217, v[66:69]
	v_mfma_f32_16x16x4_f32 v[70:73], v148, v218, v[70:73]
	v_mfma_f32_16x16x4_f32 v[74:77], v148, v219, v[74:77]
	v_mfma_f32_16x16x4_f32 v[78:81], v156, v216, v[78:81]
	v_mfma_f32_16x16x4_f32 v[82:85], v156, v217, v[82:85]
	v_mfma_f32_16x16x4_f32 v[86:89], v156, v218, v[86:89]
	v_mfma_f32_16x16x4_f32 v[90:93], v156, v219, v[90:93]
	v_mfma_f32_16x16x4_f32 v[98:101], v34, v216, v[98:101]
	v_mfma_f32_16x16x4_f32 v[102:105], v34, v217, v[102:105]
	v_mfma_f32_16x16x4_f32 v[106:109], v34, v218, v[106:109]
	v_mfma_f32_16x16x4_f32 v[110:113], v34, v219, v[110:113]
	s_waitcnt vmcnt(6)
	v_mfma_f32_16x16x4_f32 v[62:65], v149, v220, v[62:65]
	v_mfma_f32_16x16x4_f32 v[66:69], v149, v221, v[66:69]
	v_mfma_f32_16x16x4_f32 v[70:73], v149, v222, v[70:73]
	v_mfma_f32_16x16x4_f32 v[74:77], v149, v223, v[74:77]
	v_mfma_f32_16x16x4_f32 v[78:81], v157, v220, v[78:81]
	v_mfma_f32_16x16x4_f32 v[82:85], v157, v221, v[82:85]
	v_mfma_f32_16x16x4_f32 v[86:89], v157, v222, v[86:89]
	v_mfma_f32_16x16x4_f32 v[90:93], v157, v223, v[90:93]
	v_mfma_f32_16x16x4_f32 v[98:101], v35, v220, v[98:101]
	v_mfma_f32_16x16x4_f32 v[102:105], v35, v221, v[102:105]
	v_mfma_f32_16x16x4_f32 v[106:109], v35, v222, v[106:109]
	v_mfma_f32_16x16x4_f32 v[110:113], v35, v223, v[110:113]
	s_waitcnt vmcnt(5)
	v_mfma_f32_16x16x4_f32 v[62:65], v150, v224, v[62:65]
	v_mfma_f32_16x16x4_f32 v[66:69], v150, v225, v[66:69]
	v_mfma_f32_16x16x4_f32 v[70:73], v150, v226, v[70:73]
	v_mfma_f32_16x16x4_f32 v[74:77], v150, v227, v[74:77]
	v_mfma_f32_16x16x4_f32 v[78:81], v158, v224, v[78:81]
	v_mfma_f32_16x16x4_f32 v[82:85], v158, v225, v[82:85]
	v_mfma_f32_16x16x4_f32 v[86:89], v158, v226, v[86:89]
	v_mfma_f32_16x16x4_f32 v[90:93], v158, v227, v[90:93]
	v_mfma_f32_16x16x4_f32 v[98:101], v36, v224, v[98:101]
	v_mfma_f32_16x16x4_f32 v[102:105], v36, v225, v[102:105]
	v_mfma_f32_16x16x4_f32 v[106:109], v36, v226, v[106:109]
	v_mfma_f32_16x16x4_f32 v[110:113], v36, v227, v[110:113]
	s_waitcnt vmcnt(4)
; #define LAS __attribute__((address_space(3)))
; __device__ __forceinline__ void prologue_mod_item(const Args& a, LAS unsigned char* lds, int item, int tid) {
;     ...
;         for (int kk = 0; kk < 64; ++kk) { const int kl = kp * 64 + kk;
;             const float w = __builtin_nontemporal_load(&W[(size_t)(half * 512 + kl) * (6 * DM) + n0 + col]);
;             const LAS f32x4* sp = (const LAS f32x4*)(sl + kl * NSEQ);
; #pragma unroll
;             for (int q = 0; q < NSEQ / 4; ++q) { const f32x4 sv = sp[q]; const f32x2 w2 = (f32x2){w, w};
;                 acc[2 * q] = __builtin_elementwise_fma((f32x2){sv[0], sv[1]}, w2, acc[2 * q]); acc[2 * q + 1] = __builtin_elementwise_fma((f32x2){sv[2], sv[3]}, w2, acc[2 * q + 1]); } }
;     }
;     __syncthreads();
; #pragma unroll
;     for (int s = 0; s < NSEQ; ++s) sl[(kp * NSEQ + s) * 64 + col] = acc[s >> 1][s & 1];
	v_mfma_f32_16x16x4_f32 v[62:65], v151, v228, v[62:65]
	v_mfma_f32_16x16x4_f32 v[66:69], v151, v229, v[66:69]
	v_mfma_f32_16x16x4_f32 v[70:73], v151, v230, v[70:73]
	v_mfma_f32_16x16x4_f32 v[74:77], v151, v231, v[74:77]
	v_mfma_f32_16x16x4_f32 v[78:81], v159, v228, v[78:81]
	v_mfma_f32_16x16x4_f32 v[82:85], v159, v229, v[82:85]
	v_mfma_f32_16x16x4_f32 v[86:89], v159, v230, v[86:89]
	v_mfma_f32_16x16x4_f32 v[90:93], v159, v231, v[90:93]
	v_mfma_f32_16x16x4_f32 v[98:101], v37, v228, v[98:101]
	v_mfma_f32_16x16x4_f32 v[102:105], v37, v229, v[102:105]
	v_mfma_f32_16x16x4_f32 v[106:109], v37, v230, v[106:109]
	v_mfma_f32_16x16x4_f32 v[110:113], v37, v231, v[110:113]
	s_waitcnt vmcnt(3)
	v_mfma_f32_16x16x4_f32 v[62:65], v152, v232, v[62:65]
	v_mfma_f32_16x16x4_f32 v[66:69], v152, v233, v[66:69]
	v_mfma_f32_16x16x4_f32 v[70:73], v152, v234, v[70:73]
	v_mfma_f32_16x16x4_f32 v[74:77], v152, v235, v[74:77]
	v_mfma_f32_16x16x4_f32 v[78:81], v160, v232, v[78:81]
	v_mfma_f32_16x16x4_f32 v[82:85], v160, v233, v[82:85]
	v_mfma_f32_16x16x4_f32 v[86:89], v160, v234, v[86:89]
	v_mfma_f32_16x16x4_f32 v[90:93], v160, v235, v[90:93]
	v_mfma_f32_16x16x4_f32 v[98:101], v38, v232, v[98:101]
	v_mfma_f32_16x16x4_f32 v[102:105], v38, v233, v[102:105]
	v_mfma_f32_16x16x4_f32 v[106:109], v38, v234, v[106:109]
	v_mfma_f32_16x16x4_f32 v[110:113], v38, v235, v[110:113]
	s_waitcnt vmcnt(2)
	v_mfma_f32_16x16x4_f32 v[62:65], v153, v236, v[62:65]
	v_mfma_f32_16x16x4_f32 v[66:69], v153, v237, v[66:69]
	v_mfma_f32_16x16x4_f32 v[70:73], v153, v238, v[70:73]
	v_mfma_f32_16x16x4_f32 v[74:77], v153, v239, v[74:77]
	v_mfma_f32_16x16x4_f32 v[78:81], v161, v236, v[78:81]
	v_mfma_f32_16x16x4_f32 v[82:85], v161, v237, v[82:85]
	v_mfma_f32_16x16x4_f32 v[86:89], v161, v238, v[86:89]
	v_mfma_f32_16x16x4_f32 v[90:93], v161, v239, v[90:93]
	v_mfma_f32_16x16x4_f32 v[98:101], v39, v236, v[98:101]
	v_mfma_f32_16x16x4_f32 v[102:105], v39, v237, v[102:105]
	v_mfma_f32_16x16x4_f32 v[106:109], v39, v238, v[106:109]
	v_mfma_f32_16x16x4_f32 v[110:113], v39, v239, v[110:113]
	s_waitcnt vmcnt(1)
	v_mfma_f32_16x16x4_f32 v[62:65], v154, v240, v[62:65]
	v_mfma_f32_16x16x4_f32 v[66:69], v154, v241, v[66:69]
	v_mfma_f32_16x16x4_f32 v[70:73], v154, v242, v[70:73]
	v_mfma_f32_16x16x4_f32 v[74:77], v154, v243, v[74:77]
	v_mfma_f32_16x16x4_f32 v[78:81], v162, v240, v[78:81]
	v_mfma_f32_16x16x4_f32 v[82:85], v162, v241, v[82:85]
	v_mfma_f32_16x16x4_f32 v[86:89], v162, v242, v[86:89]
	v_mfma_f32_16x16x4_f32 v[90:93], v162, v243, v[90:93]
	v_mfma_f32_16x16x4_f32 v[98:101], v40, v240, v[98:101]
	v_mfma_f32_16x16x4_f32 v[102:105], v40, v241, v[102:105]
	v_mfma_f32_16x16x4_f32 v[106:109], v40, v242, v[106:109]
	v_mfma_f32_16x16x4_f32 v[110:113], v40, v243, v[110:113]
	s_waitcnt vmcnt(0)
	v_mfma_f32_16x16x4_f32 v[62:65], v155, v244, v[62:65]
	v_mfma_f32_16x16x4_f32 v[66:69], v155, v245, v[66:69]
	v_mfma_f32_16x16x4_f32 v[70:73], v155, v246, v[70:73]
	v_mfma_f32_16x16x4_f32 v[74:77], v155, v247, v[74:77]
	v_mfma_f32_16x16x4_f32 v[78:81], v163, v244, v[78:81]
	v_mfma_f32_16x16x4_f32 v[82:85], v163, v245, v[82:85]
	v_mfma_f32_16x16x4_f32 v[86:89], v163, v246, v[86:89]
	v_mfma_f32_16x16x4_f32 v[90:93], v163, v247, v[90:93]
	v_mfma_f32_16x16x4_f32 v[98:101], v41, v244, v[98:101]
	v_mfma_f32_16x16x4_f32 v[102:105], v41, v245, v[102:105]
	v_mfma_f32_16x16x4_f32 v[106:109], v41, v246, v[106:109]
	v_mfma_f32_16x16x4_f32 v[110:113], v41, v247, v[110:113]
	s_nop 11
	s_barrier
	ds_write_b128 v207, v[62:65]
	ds_write_b128 v207, v[66:69] offset:208
	ds_write_b128 v207, v[70:73] offset:416
	ds_write_b128 v207, v[74:77] offset:624
	ds_write_b128 v207, v[78:81] offset:64
	ds_write_b128 v207, v[82:85] offset:272
	ds_write_b128 v207, v[86:89] offset:480
	ds_write_b128 v207, v[90:93] offset:688
	ds_write_b128 v207, v[98:101] offset:128
	ds_write_b128 v207, v[102:105] offset:336
	ds_write_b128 v207, v[106:109] offset:544
	ds_write_b128 v207, v[110:113] offset:752
	s_waitcnt lgkmcnt(0)
	s_barrier
; __device__ __forceinline__ void prologue_mod_item(const Args& a, LAS unsigned char* lds, int item, int tid) {
;     ...
;     for (int s = 0; s < NSEQ; ++s) sl[(kp * NSEQ + s) * 64 + col] = acc[s >> 1][s & 1];
;     __syncthreads();
;     float* mod = (float*)(a.ws + WS_MOD) + (size_t)l * NSEQ * (6 * DM);
;     for (int o = tid; o < NSEQ * 64; o += 512) { const int s = o >> 6, c = o & 63; float v = a.in[10][l * (6 * DM) + n0 + c];
; #pragma unroll
;         for (int p = 0; p < 8; ++p) v += sl[(p * NSEQ + s) * 64 + c];
;         mod[(size_t)s * (6 * DM) + n0 + c] = v; }
;     __syncthreads();
	ds_read_b128 v[168:171], v208
	ds_read_b128 v[172:175], v208 offset:13312
	ds_read_b128 v[176:179], v208 offset:26624
	ds_read_b128 v[180:183], v208 offset:39936
	ds_read_b128 v[184:187], v209
	ds_read_b128 v[188:191], v209 offset:13312
	ds_read_b128 v[192:195], v209 offset:26624
	ds_read_b128 v[196:199], v209 offset:39936
	s_waitcnt lgkmcnt(7)
	v_add_f32_e32 v250, v211, v168
	v_add_f32_e32 v251, v211, v169
	v_add_f32_e32 v42, v211, v170
	v_add_f32_e32 v43, v211, v171
	s_waitcnt lgkmcnt(6)
	v_add_f32_e32 v250, v250, v172
	v_add_f32_e32 v251, v251, v173
	v_add_f32_e32 v42, v42, v174
	v_add_f32_e32 v43, v43, v175
	s_waitcnt lgkmcnt(5)
	v_add_f32_e32 v250, v250, v176
	v_add_f32_e32 v251, v251, v177
	v_add_f32_e32 v42, v42, v178
	v_add_f32_e32 v43, v43, v179
	s_waitcnt lgkmcnt(4)
	v_add_f32_e32 v250, v250, v180
	v_add_f32_e32 v251, v251, v181
	v_add_f32_e32 v42, v42, v182
	v_add_f32_e32 v43, v43, v183
	s_waitcnt lgkmcnt(3)
	v_add_f32_e32 v250, v250, v184
	v_add_f32_e32 v251, v251, v185
	v_add_f32_e32 v42, v42, v186
	v_add_f32_e32 v43, v43, v187
	s_waitcnt lgkmcnt(2)
	v_add_f32_e32 v250, v250, v188
	v_add_f32_e32 v251, v251, v189
	v_add_f32_e32 v42, v42, v190
	v_add_f32_e32 v43, v43, v191
	s_waitcnt lgkmcnt(1)
	v_add_f32_e32 v250, v250, v192
	v_add_f32_e32 v251, v251, v193
	v_add_f32_e32 v42, v42, v194
	v_add_f32_e32 v43, v43, v195
	s_waitcnt lgkmcnt(0)
	v_add_f32_e32 v250, v250, v196
	v_add_f32_e32 v251, v251, v197
	v_add_f32_e32 v42, v42, v198
	v_add_f32_e32 v43, v43, v199
	s_mov_b32 s12, s10
	s_mov_b32 s13, s11
	global_store_dword v210, v250, s[12:13]
	s_add_u32 s12, s12, 0x6000
	s_addc_u32 s13, s13, 0
	global_store_dword v210, v251, s[12:13]
	s_add_u32 s12, s12, 0x6000
	s_addc_u32 s13, s13, 0
	global_store_dword v210, v42, s[12:13]
	s_add_u32 s12, s12, 0x6000
	s_addc_u32 s13, s13, 0
	global_store_dword v210, v43, s[12:13]
	s_cmp_gt_u32 s3, 3
	s_cbranch_scc1 .Lmod_red_done
	ds_read_b128 v[168:171], v208 offset:128
	ds_read_b128 v[172:175], v208 offset:13440
	ds_read_b128 v[176:179], v208 offset:26752
	ds_read_b128 v[180:183], v208 offset:40064
	ds_read_b128 v[184:187], v209 offset:128
	ds_read_b128 v[188:191], v209 offset:13440
	ds_read_b128 v[192:195], v209 offset:26752
	ds_read_b128 v[196:199], v209 offset:40064
	s_waitcnt lgkmcnt(7)
	v_add_f32_e32 v250, v211, v168
	v_add_f32_e32 v251, v211, v169
	v_add_f32_e32 v42, v211, v170
	v_add_f32_e32 v43, v211, v171
	s_waitcnt lgkmcnt(6)
	v_add_f32_e32 v250, v250, v172
	v_add_f32_e32 v251, v251, v173
	v_add_f32_e32 v42, v42, v174
	v_add_f32_e32 v43, v43, v175
	s_waitcnt lgkmcnt(5)
	v_add_f32_e32 v250, v250, v176
	v_add_f32_e32 v251, v251, v177
	v_add_f32_e32 v42, v42, v178
	v_add_f32_e32 v43, v43, v179
	s_waitcnt lgkmcnt(4)
	v_add_f32_e32 v250, v250, v180
	v_add_f32_e32 v251, v251, v181
	v_add_f32_e32 v42, v42, v182
	v_add_f32_e32 v43, v43, v183
	s_waitcnt lgkmcnt(3)
	v_add_f32_e32 v250, v250, v184
	v_add_f32_e32 v251, v251, v185
	v_add_f32_e32 v42, v42, v186
	v_add_f32_e32 v43, v43, v187
	s_waitcnt lgkmcnt(2)
	v_add_f32_e32 v250, v250, v188
	v_add_f32_e32 v251, v251, v189
	v_add_f32_e32 v42, v42, v190
	v_add_f32_e32 v43, v43, v191
	s_waitcnt lgkmcnt(1)
	v_add_f32_e32 v250, v250, v192
	v_add_f32_e32 v251, v251, v193
	v_add_f32_e32 v42, v42, v194
	v_add_f32_e32 v43, v43, v195
	s_waitcnt lgkmcnt(0)
	v_add_f32_e32 v250, v250, v196
	v_add_f32_e32 v251, v251, v197
	v_add_f32_e32 v42, v42, v198
	v_add_f32_e32 v43, v43, v199
	s_add_u32 s12, s10, 0xc0000
	s_addc_u32 s13, s11, 0
	global_store_dword v210, v250, s[12:13]
	s_add_u32 s12, s12, 0x6000
	s_addc_u32 s13, s13, 0
	global_store_dword v210, v251, s[12:13]
	s_add_u32 s12, s12, 0x6000
	s_addc_u32 s13, s13, 0
	global_store_dword v210, v42, s[12:13]
	s_add_u32 s12, s12, 0x6000
	s_addc_u32 s13, s13, 0
	global_store_dword v210, v43, s[12:13]
.Lmod_red_done:
	v_readlane_b32 s6, v252, 0
	s_add_i32 s15, s15, s6
	s_cmpk_gt_i32 s15, 0xbf
	s_waitcnt vmcnt(0) lgkmcnt(0)
	s_barrier
	s_cbranch_scc0 .Lmod_item
